# k29 + s_setprio 1 for the latent (1280-key) items of the MLA attention phase, reset at item end
# speedup vs baseline: 1.0046x; 1.0046x over previous
.LBB0_353:
	s_waitcnt lgkmcnt(0)
	v_add_f32_e32 v55, v52, v49
	v_div_scale_f32 v52, s[4:5], v53, v53, 1.0
	v_rcp_f32_e32 v54, v52
	v_lshlrev_b32_e32 v50, 8, v48
	v_mov_b32_e32 v51, v177
	v_lshl_add_u64 v[48:49], s[0:1], 0, v[50:51]
	v_fma_f32 v56, -v52, v54, 1.0
	v_fmac_f32_e32 v54, v56, v54
	v_div_scale_f32 v56, vcc, 1.0, v53, 1.0
	v_mul_f32_e32 v57, v56, v54
	v_fma_f32 v58, -v52, v57, v56
	v_fmac_f32_e32 v57, v58, v54
	v_fma_f32 v52, -v52, v57, v56
	v_div_fmas_f32 v52, v52, v54, v57
	v_lshl_add_u64 v[50:51], s[2:3], 0, v[50:51]
	v_div_fixup_f32 v54, v52, v53, 1.0
	v_lshlrev_b64 v[52:53], 11, v[150:151]
	v_lshl_add_u64 v[56:57], v[48:49], 0, v[52:53]
	v_lshl_add_u64 v[68:69], v[50:51], 0, v[52:53]
	v_lshlrev_b64 v[52:53], 1, v[176:177]
	v_lshl_add_u64 v[58:59], v[56:57], 0, v[52:53]
	global_load_dwordx2 v[56:57], v[58:59], off
	v_pk_mul_f32 v[70:71], v[114:115], v[54:55] op_sel_hi:[1,0]
	v_pk_mul_f32 v[72:73], v[112:113], v[54:55] op_sel_hi:[1,0]
	v_pk_mul_f32 v[66:67], v[54:55], v[66:67] op_sel_hi:[0,1]
	v_pk_mul_f32 v[64:65], v[54:55], v[64:65] op_sel_hi:[0,1]
	v_pk_mul_f32 v[34:35], v[54:55], v[34:35] op_sel_hi:[0,1]
	v_pk_mul_f32 v[32:33], v[54:55], v[32:33] op_sel_hi:[0,1]
	v_pk_mul_f32 v[36:37], v[54:55], v[36:37] op_sel_hi:[0,1]
	s_waitcnt vmcnt(0)
	v_lshlrev_b32_e32 v74, 16, v56
	v_and_b32_e32 v75, 0xffff0000, v56
	v_lshlrev_b32_e32 v56, 16, v57
	v_and_b32_e32 v57, 0xffff0000, v57
	v_pk_mul_f32 v[72:73], v[72:73], v[74:75]
	v_pk_mul_f32 v[70:71], v[70:71], v[56:57]
	v_lshl_add_u64 v[56:57], v[68:69], 0, v[52:53]
	v_cvt_pk_bf16_f32 v68, v72, v73
	v_cvt_pk_bf16_f32 v69, v70, v71
	global_store_dwordx2 v[56:57], v[68:69], off
	global_load_dwordx2 v[68:69], v[58:59], off offset:32
	v_pk_mul_f32 v[70:71], v[54:55], v[86:87] op_sel_hi:[0,1]
	v_pk_mul_f32 v[72:73], v[54:55], v[84:85] op_sel_hi:[0,1]
	s_waitcnt vmcnt(0)
	v_lshlrev_b32_e32 v74, 16, v68
	v_and_b32_e32 v75, 0xffff0000, v68
	v_lshlrev_b32_e32 v68, 16, v69
	v_and_b32_e32 v69, 0xffff0000, v69
	v_pk_mul_f32 v[68:69], v[70:71], v[68:69]
	v_pk_mul_f32 v[72:73], v[72:73], v[74:75]
	v_cvt_pk_bf16_f32 v71, v68, v69
	global_load_dwordx2 v[68:69], v[58:59], off offset:64
	v_cvt_pk_bf16_f32 v70, v72, v73
	global_store_dwordx2 v[56:57], v[70:71], off offset:32
	s_waitcnt vmcnt(1)
	v_lshlrev_b32_e32 v70, 16, v68
	v_and_b32_e32 v71, 0xffff0000, v68
	v_lshlrev_b32_e32 v68, 16, v69
	v_and_b32_e32 v69, 0xffff0000, v69
	v_pk_mul_f32 v[64:65], v[64:65], v[70:71]
	v_pk_mul_f32 v[66:67], v[66:67], v[68:69]
	v_cvt_pk_bf16_f32 v64, v64, v65
	v_cvt_pk_bf16_f32 v65, v66, v67
	global_store_dwordx2 v[56:57], v[64:65], off offset:64
	global_load_dwordx2 v[64:65], v[58:59], off offset:96
	s_waitcnt vmcnt(0)
	v_lshlrev_b32_e32 v66, 16, v64
	v_and_b32_e32 v67, 0xffff0000, v64
	v_lshlrev_b32_e32 v64, 16, v65
	v_and_b32_e32 v65, 0xffff0000, v65
	v_pk_mul_f32 v[32:33], v[32:33], v[66:67]
	v_pk_mul_f32 v[34:35], v[34:35], v[64:65]
	v_cvt_pk_bf16_f32 v32, v32, v33
	v_cvt_pk_bf16_f32 v33, v34, v35
	global_store_dwordx2 v[56:57], v[32:33], off offset:96
	global_load_dwordx2 v[32:33], v[58:59], off offset:128
	v_pk_mul_f32 v[34:35], v[54:55], v[38:39] op_sel_hi:[0,1]
	s_waitcnt vmcnt(0)
	v_lshlrev_b32_e32 v38, 16, v32
	v_and_b32_e32 v39, 0xffff0000, v32
	v_lshlrev_b32_e32 v32, 16, v33
	v_and_b32_e32 v33, 0xffff0000, v33
	v_pk_mul_f32 v[32:33], v[34:35], v[32:33]
	v_pk_mul_f32 v[36:37], v[36:37], v[38:39]
	v_cvt_pk_bf16_f32 v35, v32, v33
	global_load_dwordx2 v[32:33], v[58:59], off offset:160
	v_cvt_pk_bf16_f32 v34, v36, v37
	global_store_dwordx2 v[56:57], v[34:35], off offset:128
	v_pk_mul_f32 v[34:35], v[54:55], v[62:63] op_sel_hi:[0,1]
	v_pk_mul_f32 v[36:37], v[54:55], v[60:61] op_sel_hi:[0,1]
	s_waitcnt vmcnt(1)
	v_lshlrev_b32_e32 v38, 16, v32
	v_and_b32_e32 v39, 0xffff0000, v32
	v_lshlrev_b32_e32 v32, 16, v33
	v_and_b32_e32 v33, 0xffff0000, v33
	v_pk_mul_f32 v[32:33], v[34:35], v[32:33]
	v_pk_mul_f32 v[36:37], v[36:37], v[38:39]
	v_cvt_pk_bf16_f32 v35, v32, v33
	global_load_dwordx2 v[32:33], v[58:59], off offset:192
	v_cvt_pk_bf16_f32 v34, v36, v37
	global_store_dwordx2 v[56:57], v[34:35], off offset:160
	v_pk_mul_f32 v[34:35], v[54:55], v[46:47] op_sel_hi:[0,1]
	v_pk_mul_f32 v[36:37], v[54:55], v[44:45] op_sel_hi:[0,1]
	s_waitcnt vmcnt(1)
	v_lshlrev_b32_e32 v38, 16, v32
	v_and_b32_e32 v39, 0xffff0000, v32
	v_lshlrev_b32_e32 v32, 16, v33
	v_and_b32_e32 v33, 0xffff0000, v33
	v_pk_mul_f32 v[32:33], v[34:35], v[32:33]
	v_pk_mul_f32 v[36:37], v[36:37], v[38:39]
	v_cvt_pk_bf16_f32 v35, v32, v33
	global_load_dwordx2 v[32:33], v[58:59], off offset:224
	v_cvt_pk_bf16_f32 v34, v36, v37
	global_store_dwordx2 v[56:57], v[34:35], off offset:192
	v_pk_mul_f32 v[34:35], v[54:55], v[42:43] op_sel_hi:[0,1]
	v_pk_mul_f32 v[36:37], v[54:55], v[40:41] op_sel_hi:[0,1]
	s_waitcnt vmcnt(1)
	v_lshlrev_b32_e32 v38, 16, v32
	v_and_b32_e32 v39, 0xffff0000, v32
	v_lshlrev_b32_e32 v32, 16, v33
	v_and_b32_e32 v33, 0xffff0000, v33
	v_pk_mul_f32 v[32:33], v[34:35], v[32:33]
	v_pk_mul_f32 v[36:37], v[36:37], v[38:39]
	v_cvt_pk_bf16_f32 v35, v32, v33
	v_div_scale_f32 v32, s[4:5], v55, v55, 1.0
	v_rcp_f32_e32 v33, v32
	v_cvt_pk_bf16_f32 v34, v36, v37
	global_store_dwordx2 v[56:57], v[34:35], off offset:224
	v_readlane_b32 s4, v253, 24
	v_fma_f32 v34, -v32, v33, 1.0
	v_fmac_f32_e32 v33, v34, v33
	v_div_scale_f32 v34, vcc, 1.0, v55, 1.0
	v_mul_f32_e32 v35, v34, v33
	v_fma_f32 v36, -v32, v35, v34
	v_fmac_f32_e32 v35, v36, v33
	v_fma_f32 v32, -v32, v35, v34
	v_div_fmas_f32 v32, v32, v33, v35
	v_lshlrev_b64 v[34:35], 11, v[148:149]
	v_lshl_add_u64 v[36:37], v[48:49], 0, v[34:35]
	v_lshl_add_u64 v[38:39], v[50:51], 0, v[34:35]
	v_lshl_add_u64 v[34:35], v[36:37], 0, v[52:53]
	global_load_dwordx2 v[36:37], v[34:35], off
	v_div_fixup_f32 v32, v32, v55, 1.0
	v_pk_mul_f32 v[28:29], v[32:33], v[28:29] op_sel_hi:[0,1]
	v_pk_mul_f32 v[30:31], v[32:33], v[30:31] op_sel_hi:[0,1]
	v_pk_mul_f32 v[26:27], v[32:33], v[26:27] op_sel_hi:[0,1]
	v_pk_mul_f32 v[24:25], v[32:33], v[24:25] op_sel_hi:[0,1]
	v_pk_mul_f32 v[22:23], v[32:33], v[22:23] op_sel_hi:[0,1]
	v_pk_mul_f32 v[20:21], v[32:33], v[20:21] op_sel_hi:[0,1]
	v_pk_mul_f32 v[18:19], v[32:33], v[18:19] op_sel_hi:[0,1]
	v_pk_mul_f32 v[16:17], v[32:33], v[16:17] op_sel_hi:[0,1]
	v_pk_mul_f32 v[14:15], v[32:33], v[14:15] op_sel_hi:[0,1]
	v_pk_mul_f32 v[12:13], v[32:33], v[12:13] op_sel_hi:[0,1]
	v_pk_mul_f32 v[10:11], v[32:33], v[10:11] op_sel_hi:[0,1]
	v_pk_mul_f32 v[8:9], v[32:33], v[8:9] op_sel_hi:[0,1]
	v_pk_mul_f32 v[6:7], v[32:33], v[6:7] op_sel_hi:[0,1]
	v_pk_mul_f32 v[4:5], v[32:33], v[4:5] op_sel_hi:[0,1]
	v_pk_mul_f32 v[2:3], v[32:33], v[2:3] op_sel_hi:[0,1]
	v_pk_mul_f32 v[0:1], v[32:33], v[0:1] op_sel_hi:[0,1]
	v_readlane_b32 s5, v253, 25
	s_waitcnt vmcnt(0)
	v_lshlrev_b32_e32 v40, 16, v36
	v_and_b32_e32 v41, 0xffff0000, v36
	v_pk_mul_f32 v[40:41], v[28:29], v[40:41]
	v_lshlrev_b32_e32 v28, 16, v37
	v_and_b32_e32 v29, 0xffff0000, v37
	v_pk_mul_f32 v[30:31], v[30:31], v[28:29]
	v_lshl_add_u64 v[28:29], v[38:39], 0, v[52:53]
	v_cvt_pk_bf16_f32 v37, v30, v31
	global_load_dwordx2 v[30:31], v[34:35], off offset:32
	v_cvt_pk_bf16_f32 v36, v40, v41
	global_store_dwordx2 v[28:29], v[36:37], off
	s_waitcnt vmcnt(1)
	v_lshlrev_b32_e32 v36, 16, v30
	v_and_b32_e32 v37, 0xffff0000, v30
	v_lshlrev_b32_e32 v30, 16, v31
	v_and_b32_e32 v31, 0xffff0000, v31
	v_pk_mul_f32 v[24:25], v[24:25], v[36:37]
	v_pk_mul_f32 v[26:27], v[26:27], v[30:31]
	v_cvt_pk_bf16_f32 v24, v24, v25
	v_cvt_pk_bf16_f32 v25, v26, v27
	global_store_dwordx2 v[28:29], v[24:25], off offset:32
	global_load_dwordx2 v[24:25], v[34:35], off offset:64
	s_waitcnt vmcnt(0)
	v_lshlrev_b32_e32 v26, 16, v24
	v_and_b32_e32 v27, 0xffff0000, v24
	v_lshlrev_b32_e32 v24, 16, v25
	v_and_b32_e32 v25, 0xffff0000, v25
	v_pk_mul_f32 v[20:21], v[20:21], v[26:27]
	v_pk_mul_f32 v[22:23], v[22:23], v[24:25]
	v_cvt_pk_bf16_f32 v20, v20, v21
	v_cvt_pk_bf16_f32 v21, v22, v23
	global_store_dwordx2 v[28:29], v[20:21], off offset:64
	global_load_dwordx2 v[20:21], v[34:35], off offset:96
	s_waitcnt vmcnt(0)
	v_lshlrev_b32_e32 v22, 16, v20
	v_and_b32_e32 v23, 0xffff0000, v20
	v_lshlrev_b32_e32 v20, 16, v21
	v_and_b32_e32 v21, 0xffff0000, v21
	v_pk_mul_f32 v[16:17], v[16:17], v[22:23]
	v_pk_mul_f32 v[18:19], v[18:19], v[20:21]
	v_cvt_pk_bf16_f32 v16, v16, v17
	v_cvt_pk_bf16_f32 v17, v18, v19
	global_store_dwordx2 v[28:29], v[16:17], off offset:96
	global_load_dwordx2 v[16:17], v[34:35], off offset:128
	s_waitcnt vmcnt(0)
	v_lshlrev_b32_e32 v18, 16, v16
	v_and_b32_e32 v19, 0xffff0000, v16
	v_lshlrev_b32_e32 v16, 16, v17
	v_and_b32_e32 v17, 0xffff0000, v17
	v_pk_mul_f32 v[12:13], v[12:13], v[18:19]
	v_pk_mul_f32 v[14:15], v[14:15], v[16:17]
	v_cvt_pk_bf16_f32 v12, v12, v13
	v_cvt_pk_bf16_f32 v13, v14, v15
	global_store_dwordx2 v[28:29], v[12:13], off offset:128
	global_load_dwordx2 v[12:13], v[34:35], off offset:160
	s_waitcnt vmcnt(0)
	v_lshlrev_b32_e32 v14, 16, v12
	v_and_b32_e32 v15, 0xffff0000, v12
	v_lshlrev_b32_e32 v12, 16, v13
	v_and_b32_e32 v13, 0xffff0000, v13
	v_pk_mul_f32 v[8:9], v[8:9], v[14:15]
	v_pk_mul_f32 v[10:11], v[10:11], v[12:13]
	v_cvt_pk_bf16_f32 v8, v8, v9
	v_cvt_pk_bf16_f32 v9, v10, v11
	global_store_dwordx2 v[28:29], v[8:9], off offset:160
	global_load_dwordx2 v[8:9], v[34:35], off offset:192
	s_waitcnt vmcnt(0)
	v_lshlrev_b32_e32 v10, 16, v8
	v_and_b32_e32 v11, 0xffff0000, v8
	v_lshlrev_b32_e32 v8, 16, v9
	v_and_b32_e32 v9, 0xffff0000, v9
	v_pk_mul_f32 v[4:5], v[4:5], v[10:11]
	v_pk_mul_f32 v[6:7], v[6:7], v[8:9]
	v_cvt_pk_bf16_f32 v4, v4, v5
	v_cvt_pk_bf16_f32 v5, v6, v7
	global_store_dwordx2 v[28:29], v[4:5], off offset:192
	global_load_dwordx2 v[4:5], v[34:35], off offset:224
	s_waitcnt vmcnt(0)
	v_lshlrev_b32_e32 v6, 16, v4
	v_and_b32_e32 v7, 0xffff0000, v4
	v_lshlrev_b32_e32 v4, 16, v5
	v_and_b32_e32 v5, 0xffff0000, v5
	v_pk_mul_f32 v[0:1], v[0:1], v[6:7]
	v_pk_mul_f32 v[2:3], v[2:3], v[4:5]
	v_cvt_pk_bf16_f32 v0, v0, v1
	v_cvt_pk_bf16_f32 v1, v2, v3
	global_store_dwordx2 v[28:29], v[0:1], off offset:224
	s_setprio 0
	s_load_dword s4, s[4:5], 0x0
	s_waitcnt lgkmcnt(0)
	s_add_i32 s22, s4, s22
	s_cmpk_gt_i32 s22, 0x1ff
	s_cbranch_scc1 .LBB0_385

.LBB0_370:
	s_and_b64 vcc, exec, s[4:5]
	s_cbranch_vccz .LBB0_353
	s_setprio 1
	s_ashr_i32 s4, s22, 3
	s_lshl_b32 s6, s4, 1
	s_and_b32 s5, s4, -16
	s_and_b32 s6, s6, 14
	s_or_b32 s5, s6, s5
	s_bfe_u32 s6, s4, 0x10003
	s_or_b32 s5, s5, s6
	s_cmp_lt_i32 s4, 0
	s_cselect_b32 s30, s5, s4
	s_lshl_b32 s4, s22, 5
	s_and_b32 s4, s4, 0xe0
	s_add_i32 s4, s30, s4
	s_ashr_i32 s31, s4, 6
	s_bfe_u32 s23, s4, 0x30003
	s_lshl_b32 s4, s31, 3
	s_or_b32 s6, s4, s23
	s_mul_i32 s4, s6, 0x78000
	s_mul_hi_i32 s5, s6, 0x78000
	s_add_u32 s4, s14, s4
	s_addc_u32 s5, s15, s5
	s_mul_hi_i32 s7, s6, 0x50000
	s_mul_i32 s6, s6, 0x50000
	s_add_u32 s6, s16, s6
	s_addc_u32 s7, s17, s7
	s_lshl_b32 s30, s30, 7
	s_lshl_b32 s31, s31, 10
	s_and_b32 s30, s30, 0x380
	v_mov_b32_e32 v60, v188
	s_or_b32 s30, s31, s30
	s_addk_i32 s30, 0x1000
	v_and_b32_e32 v64, 15, v60
	v_ashrrev_i32_e32 v0, 1, v60
	v_or_b32_e32 v1, s30, v64
	s_mul_i32 s30, s23, 0x180
	v_bfe_u32 v65, v60, 4, 2
	v_and_b32_e32 v0, 0xffffffe0, v0
	s_add_u32 s30, s8, s30
	v_add_u32_e32 v150, v1, v0
	s_addc_u32 s31, s9, 0
	v_lshlrev_b32_e32 v176, 4, v65
	v_lshl_add_u64 v[8:9], s[30:31], 0, v[176:177]
	s_movk_i32 s36, 0xc00
	v_or_b32_e32 v148, 16, v150
	v_mad_i64_i32 v[0:1], s[30:31], v150, s36, v[8:9]
	v_mad_i64_i32 v[8:9], s[30:31], v148, s36, v[8:9]
	s_mov_b32 s36, 0x2aaaaaab
	v_mul_hi_i32 v48, v60, s36
	s_waitcnt lgkmcnt(0)
	v_lshrrev_b32_e32 v49, 31, v48
	v_ashrrev_i32_e32 v48, 2, v48
	v_add_u32_e32 v161, v48, v49
	v_mul_lo_u32 v48, v161, 24
	v_add_u32_e32 v68, 0x100, v60
	v_add_u32_e32 v56, 0x200, v60
	v_sub_u32_e32 v78, v60, v48
	v_mul_hi_i32 v52, v68, s36
	v_mul_hi_i32 v57, v56, s36
	v_lshlrev_b32_e32 v152, 3, v78
	v_lshrrev_b32_e32 v53, 31, v52
	v_ashrrev_i32_e32 v52, 2, v52
	v_lshrrev_b32_e32 v58, 31, v57
	v_ashrrev_i32_e32 v57, 2, v57
	v_mov_b64_e32 v[70:71], s[4:5]
	v_ashrrev_i32_e32 v153, 31, v152
	v_add_u32_e32 v174, v52, v53
	v_add_u32_e32 v175, v57, v58
	v_mad_i64_i32 v[48:49], s[30:31], v161, s18, v[70:71]
	v_lshlrev_b64 v[72:73], 1, v[152:153]
	s_mul_i32 m0, s23, 0x78000
	v_cmp_le_u32_e32 vcc, 0x80, v152
	v_mov_b32_e32 v73, m0
	s_nop 1
	v_cndmask_b32_e32 v73, 0, v73, vcc
	v_sub_u32_e32 v72, v72, v73
	v_ashrrev_i32_e32 v73, 31, v72
	v_mul_lo_u32 v52, v174, 24
	v_mul_lo_u32 v57, v175, 24
	v_ashrrev_i32_e32 v61, 31, v60
	v_ashrrev_i32_e32 v69, 31, v68
	v_lshl_add_u64 v[48:49], v[48:49], 0, v[72:73]
	v_sub_u32_e32 v79, v68, v52
	v_sub_u32_e32 v80, v56, v57
	v_lshrrev_b32_e32 v61, 30, v61
	v_lshrrev_b32_e32 v69, 30, v69
	global_load_dwordx4 v[40:43], v[0:1], off
	global_load_dwordx4 v[32:35], v[0:1], off offset:64
	global_load_dwordx4 v[24:27], v[0:1], off offset:128
	global_load_dwordx4 v[16:19], v[0:1], off offset:192
	global_load_dwordx4 v[4:7], v[0:1], off offset:256
	s_nop 0
	global_load_dwordx4 v[0:3], v[0:1], off offset:320
	s_nop 0
	global_load_dwordx4 v[44:47], v[8:9], off
	global_load_dwordx4 v[36:39], v[8:9], off offset:64
	global_load_dwordx4 v[28:31], v[8:9], off offset:128
	global_load_dwordx4 v[20:23], v[8:9], off offset:192
	global_load_dwordx4 v[12:15], v[8:9], off offset:256
	s_nop 0
	global_load_dwordx4 v[8:11], v[8:9], off offset:320
	v_lshlrev_b32_e32 v154, 3, v79
	global_load_dwordx4 v[48:51], v[48:49], off
	v_lshlrev_b32_e32 v156, 3, v80
	v_add_u32_e32 v61, v60, v61
	v_add_u32_e32 v69, v68, v69
	v_ashrrev_i32_e32 v155, 31, v154
	v_ashrrev_i32_e32 v157, 31, v156
	v_ashrrev_i32_e32 v81, 2, v61
	v_and_b32_e32 v61, -4, v61
	v_ashrrev_i32_e32 v83, 2, v69
	v_and_b32_e32 v69, -4, v69
	v_mad_i64_i32 v[52:53], s[30:31], v174, s18, v[70:71]
	v_lshlrev_b64 v[74:75], 1, v[154:155]
	s_mul_i32 m0, s23, 0x78000
	v_cmp_le_u32_e32 vcc, 0x80, v154
	v_mov_b32_e32 v75, m0
	s_nop 1
	v_cndmask_b32_e32 v75, 0, v75, vcc
	v_sub_u32_e32 v74, v74, v75
	v_ashrrev_i32_e32 v75, 31, v74
	v_mad_i64_i32 v[56:57], s[30:31], v175, s18, v[70:71]
	v_lshlrev_b64 v[76:77], 1, v[156:157]
	s_mul_i32 m0, s23, 0x78000
	v_cmp_le_u32_e32 vcc, 0x80, v156
	v_mov_b32_e32 v77, m0
	s_nop 1
	v_cndmask_b32_e32 v77, 0, v77, vcc
	v_sub_u32_e32 v76, v76, v77
	v_ashrrev_i32_e32 v77, 31, v76
	v_sub_u32_e32 v82, v60, v61
	v_sub_u32_e32 v84, v68, v69
	v_lshl_add_u64 v[52:53], v[52:53], 0, v[74:75]
	v_lshl_add_u64 v[56:57], v[56:57], 0, v[76:77]
	v_mov_b64_e32 v[66:67], s[6:7]
	s_movk_i32 s30, 0xa00
	v_lshlrev_b32_e32 v158, 3, v82
	v_lshlrev_b32_e32 v164, 3, v84
	global_load_dwordx4 v[52:55], v[52:53], off
	v_mad_i64_i32 v[60:61], s[6:7], v81, s30, v[66:67]
	global_load_dwordx4 v[56:59], v[56:57], off
	v_ashrrev_i32_e32 v159, 31, v158
	v_mad_i64_i32 v[66:67], s[6:7], v83, s30, v[66:67]
	v_ashrrev_i32_e32 v165, 31, v164
	v_lshl_add_u64 v[162:163], v[158:159], 1, v[60:61]
	v_lshl_add_u64 v[166:167], v[164:165], 1, v[66:67]
	global_load_dwordx4 v[60:63], v[162:163], off
	global_load_dwordx4 v[66:69], v[166:167], off
	s_movk_i32 s6, 0xd0
	v_mul_lo_u32 v178, v161, s6
	v_lshlrev_b32_e32 v78, 4, v78
	v_lshl_add_u32 v78, v178, 1, v78
	s_barrier
	v_mul_lo_u32 v179, v174, s6
	v_mul_lo_u32 v180, v175, s6
	v_mul_lo_u32 v181, v81, 40
	v_mul_lo_u32 v182, v83, 40
	v_lshl_add_u64 v[168:169], s[4:5], 0, v[72:73]
	v_lshl_add_u64 v[170:171], s[4:5], 0, v[74:75]
	v_lshl_add_u64 v[172:173], s[4:5], 0, v[76:77]
	v_cmp_lt_i32_e32 vcc, v189, v202
	s_waitcnt vmcnt(4)
	ds_write_b128 v78, v[48:51]
	v_lshlrev_b32_e32 v48, 4, v79
	v_lshl_add_u32 v79, v179, 1, v48
	v_lshlrev_b32_e32 v48, 4, v80
	v_lshl_add_u32 v80, v180, 1, v48
	v_lshlrev_b32_e32 v48, 4, v82
	v_lshl_add_u32 v81, v181, 1, v48
	v_lshlrev_b32_e32 v48, 4, v84
	v_lshl_add_u32 v82, v182, 1, v48
	v_add_u32_e32 v48, 32, v161
	v_mad_i64_i32 v[48:49], s[6:7], v48, s18, v[70:71]
	v_lshl_add_u64 v[48:49], v[48:49], 0, v[72:73]
	global_load_dwordx4 v[48:51], v[48:49], off
	s_waitcnt vmcnt(4)
	ds_write_b128 v79, v[52:55]
	v_add_u32_e32 v52, 32, v174
	v_mad_i64_i32 v[52:53], s[6:7], v52, s18, v[70:71]
	s_waitcnt vmcnt(3)
	ds_write_b128 v80, v[56:59]
	v_add_u32_e32 v56, 32, v175
	v_mad_i64_i32 v[56:57], s[6:7], v56, s18, v[70:71]
	v_lshl_add_u64 v[52:53], v[52:53], 0, v[74:75]
	v_lshl_add_u64 v[56:57], v[56:57], 0, v[76:77]
	s_waitcnt vmcnt(2)
	ds_write_b128 v81, v[60:63] offset:13312
	s_waitcnt vmcnt(1)
	ds_write_b128 v82, v[66:69] offset:13312
	global_load_dwordx4 v[52:55], v[52:53], off
	s_nop 0
	global_load_dwordx4 v[56:59], v[56:57], off
	s_nop 0
	global_load_dwordx4 v[60:63], v[162:163], off offset:64
	global_load_dwordx4 v[66:69], v[166:167], off offset:64
	s_waitcnt lgkmcnt(0)
	s_barrier
	s_waitcnt vmcnt(4)
	ds_write_b128 v78, v[48:51] offset:23552
	s_waitcnt vmcnt(3)
	ds_write_b128 v79, v[52:55] offset:23552
	s_waitcnt vmcnt(2)
	ds_write_b128 v80, v[56:59] offset:23552
	s_waitcnt vmcnt(1)
	ds_write_b128 v81, v[60:63] offset:36864
	s_waitcnt vmcnt(0)
	ds_write_b128 v82, v[66:69] offset:36864
	v_add_u32_e32 v48, 64, v161
	v_mad_i64_i32 v[48:49], s[4:5], v48, s18, v[168:169]
	global_load_dwordx4 v[112:115], v[48:49], off
	v_add_u32_e32 v48, 64, v174
	v_mad_i64_i32 v[48:49], s[4:5], v48, s18, v[170:171]
	global_load_dwordx4 v[116:119], v[48:49], off
	v_add_u32_e32 v48, 64, v175
	v_mad_i64_i32 v[48:49], s[4:5], v48, s18, v[172:173]
	global_load_dwordx4 v[128:131], v[48:49], off
	global_load_dwordx4 v[124:127], v[162:163], off offset:128
	global_load_dwordx4 v[120:123], v[166:167], off offset:128
	v_mul_u32_u24_e32 v70, 0xd0, v64
	v_lshlrev_b32_e32 v185, 1, v70
	v_add_u32_e32 v66, 0x1a00, v185
	v_add_u32_e32 v183, v185, v176
	v_add_u32_e32 v184, v66, v176
	ds_read_b128 v[48:51], v183
	ds_read_b128 v[52:55], v184
	ds_read_b128 v[56:59], v183 offset:64
	v_cndmask_b32_e32 v71, v203, v189, vcc
	v_cmp_lt_i32_e32 vcc, v240, v202
	v_lshlrev_b32_e32 v155, 2, v71
	s_nop 0
	v_cndmask_b32_e32 v71, v203, v240, vcc
	v_lshlrev_b32_e32 v153, 2, v71
	v_readlane_b32 s4, v255, 0
	s_mov_b32 s92, s4
	s_mov_b32 s93, s4
	s_mov_b32 s94, s4
	s_mov_b32 s95, s4
	v_mov_b64_e32 v[60:61], s[92:93]
	v_readlane_b32 s5, v255, 1
	v_readlane_b32 s6, v255, 2
	v_readlane_b32 s7, v255, 3
	v_mov_b64_e32 v[62:63], s[94:95]
	v_writelane_b32 v255, s4, 0
	s_waitcnt lgkmcnt(2)
	v_mfma_f32_16x16x32_bf16 v[68:71], v[48:51], v[40:43], v[60:63]
	v_writelane_b32 v255, s5, 1
	v_writelane_b32 v255, s6, 2
	v_writelane_b32 v255, s7, 3
	v_mfma_f32_16x16x32_bf16 v[48:51], v[48:51], v[44:47], v[60:63]
	ds_read_b128 v[72:75], v184 offset:64
	s_waitcnt lgkmcnt(2)
	v_mfma_f32_16x16x32_bf16 v[76:79], v[52:55], v[40:43], v[60:63]
	v_mfma_f32_16x16x32_bf16 v[52:55], v[52:55], v[44:47], v[60:63]
	s_nop 2
	ds_read_b128 v[60:63], v183 offset:128
	s_waitcnt lgkmcnt(2)
	v_mfma_f32_16x16x32_bf16 v[68:71], v[56:59], v[32:35], v[68:71]
	v_mfma_f32_16x16x32_bf16 v[48:51], v[56:59], v[36:39], v[48:51]
	ds_read_b128 v[56:59], v184 offset:128
	s_waitcnt lgkmcnt(2)
	v_mfma_f32_16x16x32_bf16 v[52:55], v[72:75], v[36:39], v[52:55]
	v_mfma_f32_16x16x32_bf16 v[76:79], v[72:75], v[32:35], v[76:79]
	ds_read_b128 v[72:75], v183 offset:192
	s_waitcnt lgkmcnt(2)
	v_mfma_f32_16x16x32_bf16 v[68:71], v[60:63], v[24:27], v[68:71]
	v_mfma_f32_16x16x32_bf16 v[48:51], v[60:63], v[28:31], v[48:51]
	ds_read_b128 v[60:63], v184 offset:192
	s_waitcnt lgkmcnt(2)
	v_mfma_f32_16x16x32_bf16 v[52:55], v[56:59], v[28:31], v[52:55]
	v_mfma_f32_16x16x32_bf16 v[76:79], v[56:59], v[24:27], v[76:79]
	ds_read_b128 v[56:59], v183 offset:256
	s_waitcnt lgkmcnt(2)
	v_mfma_f32_16x16x32_bf16 v[68:71], v[72:75], v[16:19], v[68:71]
	v_mfma_f32_16x16x32_bf16 v[48:51], v[72:75], v[20:23], v[48:51]
	ds_read_b128 v[72:75], v184 offset:256
	s_waitcnt lgkmcnt(2)
	v_mfma_f32_16x16x32_bf16 v[52:55], v[60:63], v[20:23], v[52:55]
	v_mfma_f32_16x16x32_bf16 v[76:79], v[60:63], v[16:19], v[76:79]
	ds_read_b128 v[80:83], v183 offset:320
	s_waitcnt lgkmcnt(2)
	v_mfma_f32_16x16x32_bf16 v[60:63], v[56:59], v[4:7], v[68:71]
	v_mfma_f32_16x16x32_bf16 v[48:51], v[56:59], v[12:15], v[48:51]
	s_nop 1
	ds_read_b128 v[68:71], v184 offset:320
	s_waitcnt lgkmcnt(2)
	v_mfma_f32_16x16x32_bf16 v[56:59], v[72:75], v[4:7], v[76:79]
	v_mfma_f32_16x16x32_bf16 v[72:75], v[72:75], v[12:15], v[52:55]
	s_waitcnt lgkmcnt(1)
	v_mfma_f32_16x16x32_bf16 v[60:63], v[80:83], v[0:3], v[60:63]
	v_mfma_f32_16x16x32_bf16 v[52:55], v[80:83], v[8:11], v[48:51]
	s_waitcnt lgkmcnt(0)
	v_mfma_f32_16x16x32_bf16 v[56:59], v[68:71], v[0:3], v[56:59]
	v_mfma_f32_16x16x32_bf16 v[48:51], v[68:71], v[8:11], v[72:75]
	s_nop 3
	v_max_f32_e32 v67, v61, v61
	v_max_f32_e32 v68, v60, v60
	v_max_f32_e32 v67, v68, v67
	v_max3_f32 v67, v67, v62, v63
	v_max3_f32 v67, v67, v56, v57
	v_max3_f32 v67, v67, v58, v59
	ds_bpermute_b32 v68, v155, v67
	v_mov_b32_e32 v186, 0
	s_cmp_eq_u64 exec, 0
	v_mov_b32_e32 v187, 0
	s_waitcnt lgkmcnt(0)
	v_max_f32_e32 v68, v68, v68
	v_max_f32_e32 v67, v67, v68
	ds_bpermute_b32 v68, v153, v67
	s_cbranch_scc1 .LBB0_373
	s_waitcnt lgkmcnt(0)
	v_max_f32_e32 v68, v68, v68
	v_max_f32_e32 v67, v67, v67
	v_max_f32_e32 v67, v67, v68
	v_add_f32_e32 v187, 0, v67
	v_sub_f32_e32 v60, v60, v67
	v_sub_f32_e32 v61, v61, v67
	v_sub_f32_e32 v62, v62, v67
	v_sub_f32_e32 v63, v63, v67
	v_sub_f32_e32 v56, v56, v67
	v_sub_f32_e32 v57, v57, v67
	v_sub_f32_e32 v58, v58, v67
	v_sub_f32_e32 v59, v59, v67
